# residual-update epilogue: 128 dead lane-address instructions (left over from the ds_bpermute butterfly) removed
# baseline (speedup 1.0000x reference)
;     DI void operator()(const f32x4 (&acc)[2][2][4][2], const Unit& u, int wr, int wc, int fr, int fq) const {
;     ...
;                         ss += (x0[0] * x0[0] + x0[1] * x0[1]) + (x0[2] * x0[2] + x0[3] * x0[3]) + (x1[0] * x1[0] + x1[1] * x1[1]) + (x1[2] * x1[2] + x1[3] * x1[3]);
;                     }
;                     if (rss) { ss += __shfl_xor(ss, 16); ss += __shfl_xor(ss, 32); if (fq == 0) rss[(size_t)row * 16 + u.pn * 4 + wc] = ss; }
.LBB0_465:
	s_lshl_b32 s82, s95, 2
	s_nop 0
	v_cndmask_b32_e64 v202, 0, 1, s[52:53]
	v_cmp_ne_u32_e64 s[12:13], 1, v202
	s_andn2_b64 vcc, exec, s[52:53]
	s_ashr_i32 s83, s82, 31
	s_cbranch_vccnz .LBB0_469
	v_mul_f32_e32 v195, v195, v195
	v_fmac_f32_e32 v195, v194, v194
	v_mul_f32_e32 v194, v197, v197
	v_fmac_f32_e32 v194, v196, v196
	v_mul_f32_e32 v191, v191, v191
	v_add_f32_e32 v194, v195, v194
	v_fmac_f32_e32 v191, v190, v190
	v_mul_f32_e32 v187, v187, v187
	v_add_f32_e32 v190, v191, v194
	v_mul_f32_e32 v191, v193, v193
	v_fmac_f32_e32 v187, v186, v186
	v_mul_f32_e32 v186, v189, v189
	v_fmac_f32_e32 v191, v192, v192
	v_mul_f32_e32 v192, v199, v199
	v_fmac_f32_e32 v186, v188, v188
	v_and_b32_e32 v188, 64, v245
	v_add_f32_e32 v190, v191, v190
	v_mul_f32_e32 v191, v201, v201
	v_fmac_f32_e32 v192, v198, v198
	v_add_f32_e32 v186, v187, v186
	v_add_u32_e32 v188, 64, v188
	v_fmac_f32_e32 v191, v200, v200
	v_add_f32_e32 v186, v192, v186
	v_add_f32_e32 v186, v191, v186
	v_add_f32_e32 v186, v190, v186
	v_mov_b32_e32 v187, v186
	s_nop 1
	v_permlane16_swap_b32_e32 v187, v186
	s_waitcnt lgkmcnt(0)
	v_add_f32_e32 v186, v186, v187
	s_nop 1
	v_mov_b32_e32 v187, v186
	s_nop 1
	v_permlane32_swap_b32_e32 v187, v186
	s_and_saveexec_b64 vcc, s[4:5]
	s_cbranch_execz .LBB0_468
	v_readlane_b32 s26, v255, 5
	s_waitcnt lgkmcnt(0)
	v_add_f32_e32 v188, v186, v187
	v_lshlrev_b64 v[186:187], 6, v[234:235]
	v_readlane_b32 s27, v255, 6
	s_lshl_b32 s46, s43, 2
	s_nop 0
	v_lshl_add_u64 v[186:187], s[26:27], 0, v[186:187]
	v_lshl_add_u64 v[186:187], s[82:83], 2, v[186:187]
	v_lshl_add_u64 v[186:187], v[186:187], 0, s[46:47]
	global_store_dword v[186:187], v188, off

;     DI void operator()(const f32x4 (&acc)[2][2][4][2], const Unit& u, int wr, int wc, int fr, int fq) const {
;     ...
;                         ss += (x0[0] * x0[0] + x0[1] * x0[1]) + (x0[2] * x0[2] + x0[3] * x0[3]) + (x1[0] * x1[0] + x1[1] * x1[1]) + (x1[2] * x1[2] + x1[3] * x1[3]);
;                     }
;                     if (rss) { ss += __shfl_xor(ss, 16); ss += __shfl_xor(ss, 32); if (fq == 0) rss[(size_t)row * 16 + u.pn * 4 + wc] = ss; }
.LBB0_477:
	s_and_b64 vcc, exec, s[12:13]
	s_cbranch_vccnz .LBB0_481
	v_mul_f32_e32 v183, v183, v183
	v_fmac_f32_e32 v183, v182, v182
	v_mul_f32_e32 v182, v185, v185
	v_fmac_f32_e32 v182, v184, v184
	v_add_f32_e32 v182, v183, v182
	v_mul_f32_e32 v183, v187, v187
	v_fmac_f32_e32 v183, v186, v186
	v_mul_f32_e32 v179, v179, v179
	v_add_f32_e32 v182, v183, v182
	v_mul_f32_e32 v183, v189, v189
	v_fmac_f32_e32 v179, v178, v178
	v_mul_f32_e32 v178, v181, v181
	v_fmac_f32_e32 v183, v188, v188
	v_mul_f32_e32 v184, v191, v191
	v_fmac_f32_e32 v178, v180, v180
	v_and_b32_e32 v180, 64, v245
	v_add_f32_e32 v182, v183, v182
	v_mul_f32_e32 v183, v193, v193
	v_fmac_f32_e32 v184, v190, v190
	v_add_f32_e32 v178, v179, v178
	v_add_u32_e32 v180, 64, v180
	v_fmac_f32_e32 v183, v192, v192
	v_add_f32_e32 v178, v184, v178
	v_add_f32_e32 v178, v183, v178
	v_add_f32_e32 v178, v182, v178
	v_mov_b32_e32 v179, v178
	s_nop 1
	v_permlane16_swap_b32_e32 v179, v178
	s_waitcnt lgkmcnt(0)
	v_add_f32_e32 v178, v178, v179
	s_nop 1
	v_mov_b32_e32 v179, v178
	s_nop 1
	v_permlane32_swap_b32_e32 v179, v178
	s_and_saveexec_b64 vcc, s[4:5]
	s_cbranch_execz .LBB0_480
	v_readlane_b32 s26, v255, 5
	s_waitcnt lgkmcnt(0)
	v_add_f32_e32 v180, v178, v179
	v_lshlrev_b64 v[178:179], 6, v[232:233]
	v_readlane_b32 s27, v255, 6
	s_lshl_b32 s46, s43, 2
	s_nop 0
	v_lshl_add_u64 v[178:179], s[26:27], 0, v[178:179]
	v_lshl_add_u64 v[178:179], s[82:83], 2, v[178:179]
	v_lshl_add_u64 v[178:179], v[178:179], 0, s[46:47]
	global_store_dword v[178:179], v180, off

;     DI void operator()(const f32x4 (&acc)[2][2][4][2], const Unit& u, int wr, int wc, int fr, int fq) const {
;     ...
;                         ss += (x0[0] * x0[0] + x0[1] * x0[1]) + (x0[2] * x0[2] + x0[3] * x0[3]) + (x1[0] * x1[0] + x1[1] * x1[1]) + (x1[2] * x1[2] + x1[3] * x1[3]);
;                     }
;                     if (rss) { ss += __shfl_xor(ss, 16); ss += __shfl_xor(ss, 32); if (fq == 0) rss[(size_t)row * 16 + u.pn * 4 + wc] = ss; }
.LBB0_489:
	s_and_b64 vcc, exec, s[12:13]
	s_cbranch_vccnz .LBB0_493
	v_mul_f32_e32 v175, v175, v175
	v_fmac_f32_e32 v175, v174, v174
	v_mul_f32_e32 v174, v177, v177
	v_fmac_f32_e32 v174, v176, v176
	v_add_f32_e32 v174, v175, v174
	v_mul_f32_e32 v175, v179, v179
	v_fmac_f32_e32 v175, v178, v178
	v_mul_f32_e32 v171, v171, v171
	v_add_f32_e32 v174, v175, v174
	v_mul_f32_e32 v175, v181, v181
	v_fmac_f32_e32 v171, v170, v170
	v_mul_f32_e32 v170, v173, v173
	v_fmac_f32_e32 v175, v180, v180
	v_mul_f32_e32 v176, v183, v183
	v_fmac_f32_e32 v170, v172, v172
	v_and_b32_e32 v172, 64, v245
	v_add_f32_e32 v174, v175, v174
	v_mul_f32_e32 v175, v185, v185
	v_fmac_f32_e32 v176, v182, v182
	v_add_f32_e32 v170, v171, v170
	v_add_u32_e32 v172, 64, v172
	v_fmac_f32_e32 v175, v184, v184
	v_add_f32_e32 v170, v176, v170
	v_add_f32_e32 v170, v175, v170
	v_add_f32_e32 v170, v174, v170
	v_mov_b32_e32 v171, v170
	s_nop 1
	v_permlane16_swap_b32_e32 v171, v170
	s_waitcnt lgkmcnt(0)
	v_add_f32_e32 v170, v170, v171
	s_nop 1
	v_mov_b32_e32 v171, v170
	s_nop 1
	v_permlane32_swap_b32_e32 v171, v170
	s_and_saveexec_b64 vcc, s[4:5]
	s_cbranch_execz .LBB0_492
	v_readlane_b32 s26, v255, 5
	s_waitcnt lgkmcnt(0)
	v_add_f32_e32 v172, v170, v171
	v_lshlrev_b64 v[170:171], 6, v[230:231]
	v_readlane_b32 s27, v255, 6
	s_lshl_b32 s46, s43, 2
	s_nop 0
	v_lshl_add_u64 v[170:171], s[26:27], 0, v[170:171]
	v_lshl_add_u64 v[170:171], s[82:83], 2, v[170:171]
	v_lshl_add_u64 v[170:171], v[170:171], 0, s[46:47]
	global_store_dword v[170:171], v172, off

;     DI void operator()(const f32x4 (&acc)[2][2][4][2], const Unit& u, int wr, int wc, int fr, int fq) const {
;     ...
;                         ss += (x0[0] * x0[0] + x0[1] * x0[1]) + (x0[2] * x0[2] + x0[3] * x0[3]) + (x1[0] * x1[0] + x1[1] * x1[1]) + (x1[2] * x1[2] + x1[3] * x1[3]);
;                     }
;                     if (rss) { ss += __shfl_xor(ss, 16); ss += __shfl_xor(ss, 32); if (fq == 0) rss[(size_t)row * 16 + u.pn * 4 + wc] = ss; }
.LBB0_501:
	s_and_b64 vcc, exec, s[12:13]
	s_cbranch_vccnz .LBB0_505
	v_mul_f32_e32 v167, v167, v167
	v_fmac_f32_e32 v167, v166, v166
	v_mul_f32_e32 v166, v169, v169
	v_fmac_f32_e32 v166, v168, v168
	v_add_f32_e32 v166, v167, v166
	v_mul_f32_e32 v167, v171, v171
	v_fmac_f32_e32 v167, v170, v170
	v_mul_f32_e32 v163, v163, v163
	v_add_f32_e32 v166, v167, v166
	v_mul_f32_e32 v167, v173, v173
	v_fmac_f32_e32 v163, v162, v162
	v_mul_f32_e32 v162, v165, v165
	v_fmac_f32_e32 v167, v172, v172
	v_mul_f32_e32 v168, v175, v175
	v_fmac_f32_e32 v162, v164, v164
	v_and_b32_e32 v164, 64, v245
	v_add_f32_e32 v166, v167, v166
	v_mul_f32_e32 v167, v177, v177
	v_fmac_f32_e32 v168, v174, v174
	v_add_f32_e32 v162, v163, v162
	v_add_u32_e32 v164, 64, v164
	v_fmac_f32_e32 v167, v176, v176
	v_add_f32_e32 v162, v168, v162
	v_add_f32_e32 v162, v167, v162
	v_add_f32_e32 v162, v166, v162
	v_mov_b32_e32 v163, v162
	s_nop 1
	v_permlane16_swap_b32_e32 v163, v162
	s_waitcnt lgkmcnt(0)
	v_add_f32_e32 v162, v162, v163
	s_nop 1
	v_mov_b32_e32 v163, v162
	s_nop 1
	v_permlane32_swap_b32_e32 v163, v162
	s_and_saveexec_b64 vcc, s[4:5]
	s_cbranch_execz .LBB0_504
	v_readlane_b32 s26, v255, 5
	s_waitcnt lgkmcnt(0)
	v_add_f32_e32 v164, v162, v163
	v_lshlrev_b64 v[162:163], 6, v[228:229]
	v_readlane_b32 s27, v255, 6
	s_lshl_b32 s46, s43, 2
	s_nop 0
	v_lshl_add_u64 v[162:163], s[26:27], 0, v[162:163]
	v_lshl_add_u64 v[162:163], s[82:83], 2, v[162:163]
	v_lshl_add_u64 v[162:163], v[162:163], 0, s[46:47]
	global_store_dword v[162:163], v164, off

;     DI void operator()(const f32x4 (&acc)[2][2][4][2], const Unit& u, int wr, int wc, int fr, int fq) const {
;     ...
;                         ss += (x0[0] * x0[0] + x0[1] * x0[1]) + (x0[2] * x0[2] + x0[3] * x0[3]) + (x1[0] * x1[0] + x1[1] * x1[1]) + (x1[2] * x1[2] + x1[3] * x1[3]);
;                     }
;                     if (rss) { ss += __shfl_xor(ss, 16); ss += __shfl_xor(ss, 32); if (fq == 0) rss[(size_t)row * 16 + u.pn * 4 + wc] = ss; }
.LBB0_513:
	s_and_b64 vcc, exec, s[12:13]
	s_cbranch_vccnz .LBB0_517
	v_mul_f32_e32 v159, v159, v159
	v_fmac_f32_e32 v159, v158, v158
	v_mul_f32_e32 v158, v161, v161
	v_fmac_f32_e32 v158, v160, v160
	v_add_f32_e32 v158, v159, v158
	v_mul_f32_e32 v159, v163, v163
	v_fmac_f32_e32 v159, v162, v162
	v_mul_f32_e32 v155, v155, v155
	v_add_f32_e32 v158, v159, v158
	v_mul_f32_e32 v159, v165, v165
	v_fmac_f32_e32 v155, v154, v154
	v_mul_f32_e32 v154, v157, v157
	v_fmac_f32_e32 v159, v164, v164
	v_mul_f32_e32 v160, v167, v167
	v_fmac_f32_e32 v154, v156, v156
	v_and_b32_e32 v156, 64, v245
	v_add_f32_e32 v158, v159, v158
	v_mul_f32_e32 v159, v169, v169
	v_fmac_f32_e32 v160, v166, v166
	v_add_f32_e32 v154, v155, v154
	v_add_u32_e32 v156, 64, v156
	v_fmac_f32_e32 v159, v168, v168
	v_add_f32_e32 v154, v160, v154
	v_add_f32_e32 v154, v159, v154
	v_add_f32_e32 v154, v158, v154
	v_mov_b32_e32 v155, v154
	s_nop 1
	v_permlane16_swap_b32_e32 v155, v154
	s_waitcnt lgkmcnt(0)
	v_add_f32_e32 v154, v154, v155
	s_nop 1
	v_mov_b32_e32 v155, v154
	s_nop 1
	v_permlane32_swap_b32_e32 v155, v154
	s_and_saveexec_b64 vcc, s[4:5]
	s_cbranch_execz .LBB0_516
	v_readlane_b32 s26, v255, 5
	s_waitcnt lgkmcnt(0)
	v_add_f32_e32 v156, v154, v155
	v_lshlrev_b64 v[154:155], 6, v[226:227]
	v_readlane_b32 s27, v255, 6
	s_lshl_b32 s46, s43, 2
	s_nop 0
	v_lshl_add_u64 v[154:155], s[26:27], 0, v[154:155]
	v_lshl_add_u64 v[154:155], s[82:83], 2, v[154:155]
	v_lshl_add_u64 v[154:155], v[154:155], 0, s[46:47]
	global_store_dword v[154:155], v156, off

;     DI void operator()(const f32x4 (&acc)[2][2][4][2], const Unit& u, int wr, int wc, int fr, int fq) const {
;     ...
;                         ss += (x0[0] * x0[0] + x0[1] * x0[1]) + (x0[2] * x0[2] + x0[3] * x0[3]) + (x1[0] * x1[0] + x1[1] * x1[1]) + (x1[2] * x1[2] + x1[3] * x1[3]);
;                     }
;                     if (rss) { ss += __shfl_xor(ss, 16); ss += __shfl_xor(ss, 32); if (fq == 0) rss[(size_t)row * 16 + u.pn * 4 + wc] = ss; }
.LBB0_525:
	s_and_b64 vcc, exec, s[12:13]
	s_cbranch_vccnz .LBB0_529
	v_mul_f32_e32 v151, v151, v151
	v_fmac_f32_e32 v151, v150, v150
	v_mul_f32_e32 v150, v153, v153
	v_fmac_f32_e32 v150, v152, v152
	v_add_f32_e32 v150, v151, v150
	v_mul_f32_e32 v151, v155, v155
	v_fmac_f32_e32 v151, v154, v154
	v_mul_f32_e32 v147, v147, v147
	v_add_f32_e32 v150, v151, v150
	v_mul_f32_e32 v151, v157, v157
	v_fmac_f32_e32 v147, v146, v146
	v_mul_f32_e32 v146, v149, v149
	v_fmac_f32_e32 v151, v156, v156
	v_mul_f32_e32 v152, v159, v159
	v_fmac_f32_e32 v146, v148, v148
	v_and_b32_e32 v148, 64, v245
	v_add_f32_e32 v150, v151, v150
	v_mul_f32_e32 v151, v161, v161
	v_fmac_f32_e32 v152, v158, v158
	v_add_f32_e32 v146, v147, v146
	v_add_u32_e32 v148, 64, v148
	v_fmac_f32_e32 v151, v160, v160
	v_add_f32_e32 v146, v152, v146
	v_add_f32_e32 v146, v151, v146
	v_add_f32_e32 v146, v150, v146
	v_mov_b32_e32 v147, v146
	s_nop 1
	v_permlane16_swap_b32_e32 v147, v146
	s_waitcnt lgkmcnt(0)
	v_add_f32_e32 v146, v146, v147
	s_nop 1
	v_mov_b32_e32 v147, v146
	s_nop 1
	v_permlane32_swap_b32_e32 v147, v146
	s_and_saveexec_b64 vcc, s[4:5]
	s_cbranch_execz .LBB0_528
	v_readlane_b32 s26, v255, 5
	s_waitcnt lgkmcnt(0)
	v_add_f32_e32 v148, v146, v147
	v_lshlrev_b64 v[146:147], 6, v[224:225]
	v_readlane_b32 s27, v255, 6
	s_lshl_b32 s46, s43, 2
	s_nop 0
	v_lshl_add_u64 v[146:147], s[26:27], 0, v[146:147]
	v_lshl_add_u64 v[146:147], s[82:83], 2, v[146:147]
	v_lshl_add_u64 v[146:147], v[146:147], 0, s[46:47]
	global_store_dword v[146:147], v148, off

;     DI void operator()(const f32x4 (&acc)[2][2][4][2], const Unit& u, int wr, int wc, int fr, int fq) const {
;     ...
;                         ss += (x0[0] * x0[0] + x0[1] * x0[1]) + (x0[2] * x0[2] + x0[3] * x0[3]) + (x1[0] * x1[0] + x1[1] * x1[1]) + (x1[2] * x1[2] + x1[3] * x1[3]);
;                     }
;                     if (rss) { ss += __shfl_xor(ss, 16); ss += __shfl_xor(ss, 32); if (fq == 0) rss[(size_t)row * 16 + u.pn * 4 + wc] = ss; }
.LBB0_537:
	s_and_b64 vcc, exec, s[12:13]
	s_cbranch_vccnz .LBB0_541
	v_mul_f32_e32 v143, v143, v143
	v_fmac_f32_e32 v143, v142, v142
	v_mul_f32_e32 v142, v145, v145
	v_fmac_f32_e32 v142, v144, v144
	v_add_f32_e32 v142, v143, v142
	v_mul_f32_e32 v143, v147, v147
	v_fmac_f32_e32 v143, v146, v146
	v_mul_f32_e32 v139, v139, v139
	v_add_f32_e32 v142, v143, v142
	v_mul_f32_e32 v143, v149, v149
	v_fmac_f32_e32 v139, v138, v138
	v_mul_f32_e32 v138, v141, v141
	v_fmac_f32_e32 v143, v148, v148
	v_mul_f32_e32 v144, v151, v151
	v_fmac_f32_e32 v138, v140, v140
	v_and_b32_e32 v140, 64, v245
	v_add_f32_e32 v142, v143, v142
	v_mul_f32_e32 v143, v153, v153
	v_fmac_f32_e32 v144, v150, v150
	v_add_f32_e32 v138, v139, v138
	v_add_u32_e32 v140, 64, v140
	v_fmac_f32_e32 v143, v152, v152
	v_add_f32_e32 v138, v144, v138
	v_add_f32_e32 v138, v143, v138
	v_add_f32_e32 v138, v142, v138
	v_mov_b32_e32 v139, v138
	s_nop 1
	v_permlane16_swap_b32_e32 v139, v138
	s_waitcnt lgkmcnt(0)
	v_add_f32_e32 v138, v138, v139
	s_nop 1
	v_mov_b32_e32 v139, v138
	s_nop 1
	v_permlane32_swap_b32_e32 v139, v138
	s_and_saveexec_b64 vcc, s[4:5]
	s_cbranch_execz .LBB0_540
	v_readlane_b32 s26, v255, 5
	s_waitcnt lgkmcnt(0)
	v_add_f32_e32 v140, v138, v139
	v_lshlrev_b64 v[138:139], 6, v[222:223]
	v_readlane_b32 s27, v255, 6
	s_lshl_b32 s46, s43, 2
	s_nop 0
	v_lshl_add_u64 v[138:139], s[26:27], 0, v[138:139]
	v_lshl_add_u64 v[138:139], s[82:83], 2, v[138:139]
	v_lshl_add_u64 v[138:139], v[138:139], 0, s[46:47]
	global_store_dword v[138:139], v140, off

;     DI void operator()(const f32x4 (&acc)[2][2][4][2], const Unit& u, int wr, int wc, int fr, int fq) const {
;     ...
;                         ss += (x0[0] * x0[0] + x0[1] * x0[1]) + (x0[2] * x0[2] + x0[3] * x0[3]) + (x1[0] * x1[0] + x1[1] * x1[1]) + (x1[2] * x1[2] + x1[3] * x1[3]);
;                     }
;                     if (rss) { ss += __shfl_xor(ss, 16); ss += __shfl_xor(ss, 32); if (fq == 0) rss[(size_t)row * 16 + u.pn * 4 + wc] = ss; }
.LBB0_549:
	s_and_b64 vcc, exec, s[12:13]
	s_cbranch_vccnz .LBB0_553
	v_mul_f32_e32 v135, v135, v135
	v_fmac_f32_e32 v135, v134, v134
	v_mul_f32_e32 v134, v137, v137
	v_fmac_f32_e32 v134, v136, v136
	v_add_f32_e32 v134, v135, v134
	v_mul_f32_e32 v135, v139, v139
	v_fmac_f32_e32 v135, v138, v138
	v_mul_f32_e32 v131, v131, v131
	v_add_f32_e32 v134, v135, v134
	v_mul_f32_e32 v135, v141, v141
	v_fmac_f32_e32 v131, v130, v130
	v_mul_f32_e32 v130, v133, v133
	v_fmac_f32_e32 v135, v140, v140
	v_mul_f32_e32 v136, v143, v143
	v_fmac_f32_e32 v130, v132, v132
	v_and_b32_e32 v132, 64, v245
	v_add_f32_e32 v134, v135, v134
	v_mul_f32_e32 v135, v145, v145
	v_fmac_f32_e32 v136, v142, v142
	v_add_f32_e32 v130, v131, v130
	v_add_u32_e32 v132, 64, v132
	v_fmac_f32_e32 v135, v144, v144
	v_add_f32_e32 v130, v136, v130
	v_add_f32_e32 v130, v135, v130
	v_add_f32_e32 v130, v134, v130
	v_mov_b32_e32 v131, v130
	s_nop 1
	v_permlane16_swap_b32_e32 v131, v130
	s_waitcnt lgkmcnt(0)
	v_add_f32_e32 v130, v130, v131
	s_nop 1
	v_mov_b32_e32 v131, v130
	s_nop 1
	v_permlane32_swap_b32_e32 v131, v130
	s_and_saveexec_b64 s[10:11], s[4:5]
	s_cbranch_execz .LBB0_552
	v_readlane_b32 s12, v255, 5
	s_waitcnt lgkmcnt(0)
	v_add_f32_e32 v132, v130, v131
	v_lshlrev_b64 v[130:131], 6, v[218:219]
	v_readlane_b32 s13, v255, 6
	s_lshl_b32 s46, s43, 2
	s_nop 0
	v_lshl_add_u64 v[130:131], s[12:13], 0, v[130:131]
	v_lshl_add_u64 v[130:131], s[82:83], 2, v[130:131]
	v_lshl_add_u64 v[130:131], v[130:131], 0, s[46:47]
	global_store_dword v[130:131], v132, off

;     DI void operator()(const f32x4 (&acc)[2][2][4][2], const Unit& u, int wr, int wc, int fr, int fq) const {
;     ...
;                     ss += (x0[0] * x0[0] + x0[1] * x0[1]) + (x0[2] * x0[2] + x0[3] * x0[3]) + (x1[0] * x1[0] + x1[1] * x1[1]) + (x1[2] * x1[2] + x1[3] * x1[3]);
;                 }
;                 if (rss) { ss += __shfl_xor(ss, 16); ss += __shfl_xor(ss, 32); if (fq == 0) rss[(size_t)row * 16 + u.pn * 4 + wc] = ss; }
.LBB0_562:
	s_lshl_b32 s82, s95, 2
	v_cndmask_b32_e64 v130, 0, 1, s[52:53]
	v_cmp_ne_u32_e64 s[12:13], 1, v130
	s_andn2_b64 vcc, exec, s[52:53]
	s_ashr_i32 s83, s82, 31
	s_cbranch_vccnz .LBB0_566
	v_mul_f32_e32 v127, v127, v127
	v_mul_f32_e32 v117, v117, v117
	v_mul_f32_e32 v115, v115, v115
	v_fmac_f32_e32 v127, v126, v126
	v_mul_f32_e32 v126, v129, v129
	v_fmac_f32_e32 v117, v116, v116
	v_fmac_f32_e32 v115, v114, v114
	v_mul_f32_e32 v114, v119, v119
	v_mul_f32_e32 v116, v121, v121
	v_fmac_f32_e32 v126, v128, v128
	v_mul_f32_e32 v123, v123, v123
	v_fmac_f32_e32 v114, v118, v118
	v_fmac_f32_e32 v116, v120, v120
	v_add_f32_e32 v126, v127, v126
	v_fmac_f32_e32 v123, v122, v122
	v_add_f32_e32 v114, v114, v116
	v_and_b32_e32 v116, 64, v245
	v_add_f32_e32 v122, v123, v126
	v_mul_f32_e32 v123, v125, v125
	v_add_f32_e32 v114, v115, v114
	v_add_u32_e32 v116, 64, v116
	v_fmac_f32_e32 v123, v124, v124
	v_add_f32_e32 v122, v123, v122
	v_add_f32_e32 v114, v117, v114
	v_add_f32_e32 v114, v122, v114
	v_mov_b32_e32 v115, v114
	s_nop 1
	v_permlane16_swap_b32_e32 v115, v114
	s_waitcnt lgkmcnt(0)
	v_add_f32_e32 v114, v114, v115
	s_nop 1
	v_mov_b32_e32 v115, v114
	s_nop 1
	v_permlane32_swap_b32_e32 v115, v114
	s_and_saveexec_b64 vcc, s[4:5]
	s_cbranch_execz .LBB0_565
	v_readlane_b32 s26, v255, 5
	s_waitcnt lgkmcnt(0)
	v_add_f32_e32 v116, v114, v115
	v_lshlrev_b64 v[114:115], 6, v[234:235]
	v_readlane_b32 s27, v255, 6
	s_lshl_b32 s46, s43, 2
	s_nop 0
	v_lshl_add_u64 v[114:115], s[26:27], 0, v[114:115]
	v_lshl_add_u64 v[114:115], s[82:83], 2, v[114:115]
	v_lshl_add_u64 v[114:115], v[114:115], 0, s[46:47]
	global_store_dword v[114:115], v116, off

;     DI void operator()(const f32x4 (&acc)[2][2][4][2], const Unit& u, int wr, int wc, int fr, int fq) const {
;     ...
;                     ss += (x0[0] * x0[0] + x0[1] * x0[1]) + (x0[2] * x0[2] + x0[3] * x0[3]) + (x1[0] * x1[0] + x1[1] * x1[1]) + (x1[2] * x1[2] + x1[3] * x1[3]);
;                 }
;                 if (rss) { ss += __shfl_xor(ss, 16); ss += __shfl_xor(ss, 32); if (fq == 0) rss[(size_t)row * 16 + u.pn * 4 + wc] = ss; }
.LBB0_574:
	s_and_b64 vcc, exec, s[12:13]
	s_cbranch_vccnz .LBB0_578
	v_mul_f32_e32 v111, v111, v111
	v_mul_f32_e32 v101, v101, v101
	v_mul_f32_e32 v99, v99, v99
	v_fmac_f32_e32 v111, v110, v110
	v_mul_f32_e32 v110, v113, v113
	v_fmac_f32_e32 v101, v100, v100
	v_fmac_f32_e32 v99, v98, v98
	v_mul_f32_e32 v98, v103, v103
	v_mul_f32_e32 v100, v105, v105
	v_fmac_f32_e32 v110, v112, v112
	v_mul_f32_e32 v107, v107, v107
	v_fmac_f32_e32 v98, v102, v102
	v_fmac_f32_e32 v100, v104, v104
	v_add_f32_e32 v110, v111, v110
	v_fmac_f32_e32 v107, v106, v106
	v_add_f32_e32 v98, v98, v100
	v_and_b32_e32 v100, 64, v245
	v_add_f32_e32 v106, v107, v110
	v_mul_f32_e32 v107, v109, v109
	v_add_f32_e32 v98, v99, v98
	v_add_u32_e32 v100, 64, v100
	v_fmac_f32_e32 v107, v108, v108
	v_add_f32_e32 v106, v107, v106
	v_add_f32_e32 v98, v101, v98
	v_add_f32_e32 v98, v106, v98
	v_mov_b32_e32 v99, v98
	s_nop 1
	v_permlane16_swap_b32_e32 v99, v98
	s_waitcnt lgkmcnt(0)
	v_add_f32_e32 v98, v98, v99
	s_nop 1
	v_mov_b32_e32 v99, v98
	s_nop 1
	v_permlane32_swap_b32_e32 v99, v98
	s_and_saveexec_b64 vcc, s[4:5]
	s_cbranch_execz .LBB0_577
	v_readlane_b32 s26, v255, 5
	s_waitcnt lgkmcnt(0)
	v_add_f32_e32 v100, v98, v99
	v_lshlrev_b64 v[98:99], 6, v[232:233]
	v_readlane_b32 s27, v255, 6
	s_lshl_b32 s46, s43, 2
	s_nop 0
	v_lshl_add_u64 v[98:99], s[26:27], 0, v[98:99]
	v_lshl_add_u64 v[98:99], s[82:83], 2, v[98:99]
	v_lshl_add_u64 v[98:99], v[98:99], 0, s[46:47]
	global_store_dword v[98:99], v100, off

;     DI void operator()(const f32x4 (&acc)[2][2][4][2], const Unit& u, int wr, int wc, int fr, int fq) const {
;     ...
;                     ss += (x0[0] * x0[0] + x0[1] * x0[1]) + (x0[2] * x0[2] + x0[3] * x0[3]) + (x1[0] * x1[0] + x1[1] * x1[1]) + (x1[2] * x1[2] + x1[3] * x1[3]);
;                 }
;                 if (rss) { ss += __shfl_xor(ss, 16); ss += __shfl_xor(ss, 32); if (fq == 0) rss[(size_t)row * 16 + u.pn * 4 + wc] = ss; }
.LBB0_586:
	s_and_b64 vcc, exec, s[12:13]
	s_cbranch_vccnz .LBB0_590
	v_mul_f32_e32 v95, v95, v95
	v_mul_f32_e32 v85, v85, v85
	v_mul_f32_e32 v83, v83, v83
	v_fmac_f32_e32 v95, v94, v94
	v_mul_f32_e32 v94, v97, v97
	v_fmac_f32_e32 v85, v84, v84
	v_fmac_f32_e32 v83, v82, v82
	v_mul_f32_e32 v82, v87, v87
	v_mul_f32_e32 v84, v89, v89
	v_fmac_f32_e32 v94, v96, v96
	v_mul_f32_e32 v91, v91, v91
	v_fmac_f32_e32 v82, v86, v86
	v_fmac_f32_e32 v84, v88, v88
	v_add_f32_e32 v94, v95, v94
	v_fmac_f32_e32 v91, v90, v90
	v_add_f32_e32 v82, v82, v84
	v_and_b32_e32 v84, 64, v245
	v_add_f32_e32 v90, v91, v94
	v_mul_f32_e32 v91, v93, v93
	v_add_f32_e32 v82, v83, v82
	v_add_u32_e32 v84, 64, v84
	v_fmac_f32_e32 v91, v92, v92
	v_add_f32_e32 v90, v91, v90
	v_add_f32_e32 v82, v85, v82
	v_add_f32_e32 v82, v90, v82
	v_mov_b32_e32 v83, v82
	s_nop 1
	v_permlane16_swap_b32_e32 v83, v82
	s_waitcnt lgkmcnt(0)
	v_add_f32_e32 v82, v82, v83
	s_nop 1
	v_mov_b32_e32 v83, v82
	s_nop 1
	v_permlane32_swap_b32_e32 v83, v82
	s_and_saveexec_b64 vcc, s[4:5]
	s_cbranch_execz .LBB0_589
	v_readlane_b32 s26, v255, 5
	s_waitcnt lgkmcnt(0)
	v_add_f32_e32 v84, v82, v83
	v_lshlrev_b64 v[82:83], 6, v[230:231]
	v_readlane_b32 s27, v255, 6
	s_lshl_b32 s46, s43, 2
	s_nop 0
	v_lshl_add_u64 v[82:83], s[26:27], 0, v[82:83]
	v_lshl_add_u64 v[82:83], s[82:83], 2, v[82:83]
	v_lshl_add_u64 v[82:83], v[82:83], 0, s[46:47]
	global_store_dword v[82:83], v84, off

;     DI void operator()(const f32x4 (&acc)[2][2][4][2], const Unit& u, int wr, int wc, int fr, int fq) const {
;     ...
;                     ss += (x0[0] * x0[0] + x0[1] * x0[1]) + (x0[2] * x0[2] + x0[3] * x0[3]) + (x1[0] * x1[0] + x1[1] * x1[1]) + (x1[2] * x1[2] + x1[3] * x1[3]);
;                 }
;                 if (rss) { ss += __shfl_xor(ss, 16); ss += __shfl_xor(ss, 32); if (fq == 0) rss[(size_t)row * 16 + u.pn * 4 + wc] = ss; }
.LBB0_598:
	s_and_b64 vcc, exec, s[12:13]
	s_cbranch_vccnz .LBB0_602
	v_mul_f32_e32 v79, v79, v79
	v_mul_f32_e32 v69, v69, v69
	v_mul_f32_e32 v67, v67, v67
	v_fmac_f32_e32 v79, v78, v78
	v_mul_f32_e32 v78, v81, v81
	v_fmac_f32_e32 v69, v68, v68
	v_fmac_f32_e32 v67, v66, v66
	v_mul_f32_e32 v66, v71, v71
	v_mul_f32_e32 v68, v73, v73
	v_fmac_f32_e32 v78, v80, v80
	v_mul_f32_e32 v75, v75, v75
	v_fmac_f32_e32 v66, v70, v70
	v_fmac_f32_e32 v68, v72, v72
	v_add_f32_e32 v78, v79, v78
	v_fmac_f32_e32 v75, v74, v74
	v_add_f32_e32 v66, v66, v68
	v_and_b32_e32 v68, 64, v245
	v_add_f32_e32 v74, v75, v78
	v_mul_f32_e32 v75, v77, v77
	v_add_f32_e32 v66, v67, v66
	v_add_u32_e32 v68, 64, v68
	v_fmac_f32_e32 v75, v76, v76
	v_add_f32_e32 v74, v75, v74
	v_add_f32_e32 v66, v69, v66
	v_add_f32_e32 v66, v74, v66
	v_mov_b32_e32 v67, v66
	s_nop 1
	v_permlane16_swap_b32_e32 v67, v66
	s_waitcnt lgkmcnt(0)
	v_add_f32_e32 v66, v66, v67
	s_nop 1
	v_mov_b32_e32 v67, v66
	s_nop 1
	v_permlane32_swap_b32_e32 v67, v66
	s_and_saveexec_b64 vcc, s[4:5]
	s_cbranch_execz .LBB0_601
	v_readlane_b32 s26, v255, 5
	s_waitcnt lgkmcnt(0)
	v_add_f32_e32 v68, v66, v67
	v_lshlrev_b64 v[66:67], 6, v[228:229]
	v_readlane_b32 s27, v255, 6
	s_lshl_b32 s46, s43, 2
	s_nop 0
	v_lshl_add_u64 v[66:67], s[26:27], 0, v[66:67]
	v_lshl_add_u64 v[66:67], s[82:83], 2, v[66:67]
	v_lshl_add_u64 v[66:67], v[66:67], 0, s[46:47]
	global_store_dword v[66:67], v68, off

;     DI void operator()(const f32x4 (&acc)[2][2][4][2], const Unit& u, int wr, int wc, int fr, int fq) const {
;     ...
;                     ss += (x0[0] * x0[0] + x0[1] * x0[1]) + (x0[2] * x0[2] + x0[3] * x0[3]) + (x1[0] * x1[0] + x1[1] * x1[1]) + (x1[2] * x1[2] + x1[3] * x1[3]);
;                 }
;                 if (rss) { ss += __shfl_xor(ss, 16); ss += __shfl_xor(ss, 32); if (fq == 0) rss[(size_t)row * 16 + u.pn * 4 + wc] = ss; }
.LBB0_610:
	s_and_b64 vcc, exec, s[12:13]
	s_cbranch_vccnz .LBB0_614
	v_mul_f32_e32 v63, v63, v63
	v_mul_f32_e32 v53, v53, v53
	v_mul_f32_e32 v51, v51, v51
	v_fmac_f32_e32 v63, v62, v62
	v_mul_f32_e32 v62, v65, v65
	v_fmac_f32_e32 v53, v52, v52
	v_fmac_f32_e32 v51, v50, v50
	v_mul_f32_e32 v50, v55, v55
	v_mul_f32_e32 v52, v57, v57
	v_fmac_f32_e32 v62, v64, v64
	v_mul_f32_e32 v59, v59, v59
	v_fmac_f32_e32 v50, v54, v54
	v_fmac_f32_e32 v52, v56, v56
	v_add_f32_e32 v62, v63, v62
	v_fmac_f32_e32 v59, v58, v58
	v_add_f32_e32 v50, v50, v52
	v_and_b32_e32 v52, 64, v245
	v_add_f32_e32 v58, v59, v62
	v_mul_f32_e32 v59, v61, v61
	v_add_f32_e32 v50, v51, v50
	v_add_u32_e32 v52, 64, v52
	v_fmac_f32_e32 v59, v60, v60
	v_add_f32_e32 v58, v59, v58
	v_add_f32_e32 v50, v53, v50
	v_add_f32_e32 v50, v58, v50
	v_mov_b32_e32 v51, v50
	s_nop 1
	v_permlane16_swap_b32_e32 v51, v50
	s_waitcnt lgkmcnt(0)
	v_add_f32_e32 v50, v50, v51
	s_nop 1
	v_mov_b32_e32 v51, v50
	s_nop 1
	v_permlane32_swap_b32_e32 v51, v50
	s_and_saveexec_b64 vcc, s[4:5]
	s_cbranch_execz .LBB0_613
	v_readlane_b32 s26, v255, 5
	s_waitcnt lgkmcnt(0)
	v_add_f32_e32 v52, v50, v51
	v_lshlrev_b64 v[50:51], 6, v[226:227]
	v_readlane_b32 s27, v255, 6
	s_lshl_b32 s46, s43, 2
	s_nop 0
	v_lshl_add_u64 v[50:51], s[26:27], 0, v[50:51]
	v_lshl_add_u64 v[50:51], s[82:83], 2, v[50:51]
	v_lshl_add_u64 v[50:51], v[50:51], 0, s[46:47]
	global_store_dword v[50:51], v52, off

;     DI void operator()(const f32x4 (&acc)[2][2][4][2], const Unit& u, int wr, int wc, int fr, int fq) const {
;     ...
;                     ss += (x0[0] * x0[0] + x0[1] * x0[1]) + (x0[2] * x0[2] + x0[3] * x0[3]) + (x1[0] * x1[0] + x1[1] * x1[1]) + (x1[2] * x1[2] + x1[3] * x1[3]);
;                 }
;                 if (rss) { ss += __shfl_xor(ss, 16); ss += __shfl_xor(ss, 32); if (fq == 0) rss[(size_t)row * 16 + u.pn * 4 + wc] = ss; }
.LBB0_622:
	s_and_b64 vcc, exec, s[12:13]
	s_cbranch_vccnz .LBB0_626
	v_mul_f32_e32 v47, v47, v47
	v_mul_f32_e32 v37, v37, v37
	v_mul_f32_e32 v35, v35, v35
	v_fmac_f32_e32 v47, v46, v46
	v_mul_f32_e32 v46, v49, v49
	v_fmac_f32_e32 v37, v36, v36
	v_fmac_f32_e32 v35, v34, v34
	v_mul_f32_e32 v34, v39, v39
	v_mul_f32_e32 v36, v41, v41
	v_fmac_f32_e32 v46, v48, v48
	v_mul_f32_e32 v43, v43, v43
	v_fmac_f32_e32 v34, v38, v38
	v_fmac_f32_e32 v36, v40, v40
	v_add_f32_e32 v46, v47, v46
	v_fmac_f32_e32 v43, v42, v42
	v_add_f32_e32 v34, v34, v36
	v_and_b32_e32 v36, 64, v245
	v_add_f32_e32 v42, v43, v46
	v_mul_f32_e32 v43, v45, v45
	v_add_f32_e32 v34, v35, v34
	v_add_u32_e32 v36, 64, v36
	v_fmac_f32_e32 v43, v44, v44
	v_add_f32_e32 v42, v43, v42
	v_add_f32_e32 v34, v37, v34
	v_add_f32_e32 v34, v42, v34
	v_mov_b32_e32 v35, v34
	s_nop 1
	v_permlane16_swap_b32_e32 v35, v34
	s_waitcnt lgkmcnt(0)
	v_add_f32_e32 v34, v34, v35
	s_nop 1
	v_mov_b32_e32 v35, v34
	s_nop 1
	v_permlane32_swap_b32_e32 v35, v34
	s_and_saveexec_b64 vcc, s[4:5]
	s_cbranch_execz .LBB0_625
	v_readlane_b32 s26, v255, 5
	s_waitcnt lgkmcnt(0)
	v_add_f32_e32 v36, v34, v35
	v_lshlrev_b64 v[34:35], 6, v[224:225]
	v_readlane_b32 s27, v255, 6
	s_lshl_b32 s46, s43, 2
	s_nop 0
	v_lshl_add_u64 v[34:35], s[26:27], 0, v[34:35]
	v_lshl_add_u64 v[34:35], s[82:83], 2, v[34:35]
	v_lshl_add_u64 v[34:35], v[34:35], 0, s[46:47]
	global_store_dword v[34:35], v36, off

;     DI void operator()(const f32x4 (&acc)[2][2][4][2], const Unit& u, int wr, int wc, int fr, int fq) const {
;     ...
;                     ss += (x0[0] * x0[0] + x0[1] * x0[1]) + (x0[2] * x0[2] + x0[3] * x0[3]) + (x1[0] * x1[0] + x1[1] * x1[1]) + (x1[2] * x1[2] + x1[3] * x1[3]);
;                 }
;                 if (rss) { ss += __shfl_xor(ss, 16); ss += __shfl_xor(ss, 32); if (fq == 0) rss[(size_t)row * 16 + u.pn * 4 + wc] = ss; }
.LBB0_634:
	s_and_b64 vcc, exec, s[12:13]
	s_cbranch_vccnz .LBB0_638
	v_mul_f32_e32 v31, v31, v31
	v_mul_f32_e32 v21, v21, v21
	v_mul_f32_e32 v19, v19, v19
	v_fmac_f32_e32 v31, v30, v30
	v_mul_f32_e32 v30, v33, v33
	v_fmac_f32_e32 v21, v20, v20
	v_fmac_f32_e32 v19, v18, v18
	v_mul_f32_e32 v18, v23, v23
	v_mul_f32_e32 v20, v25, v25
	v_fmac_f32_e32 v30, v32, v32
	v_mul_f32_e32 v27, v27, v27
	v_fmac_f32_e32 v18, v22, v22
	v_fmac_f32_e32 v20, v24, v24
	v_add_f32_e32 v30, v31, v30
	v_fmac_f32_e32 v27, v26, v26
	v_add_f32_e32 v18, v18, v20
	v_and_b32_e32 v20, 64, v245
	v_add_f32_e32 v26, v27, v30
	v_mul_f32_e32 v27, v29, v29
	v_add_f32_e32 v18, v19, v18
	v_add_u32_e32 v20, 64, v20
	v_fmac_f32_e32 v27, v28, v28
	v_add_f32_e32 v26, v27, v26
	v_add_f32_e32 v18, v21, v18
	v_add_f32_e32 v18, v26, v18
	v_mov_b32_e32 v19, v18
	s_nop 1
	v_permlane16_swap_b32_e32 v19, v18
	s_waitcnt lgkmcnt(0)
	v_add_f32_e32 v18, v18, v19
	s_nop 1
	v_mov_b32_e32 v19, v18
	s_nop 1
	v_permlane32_swap_b32_e32 v19, v18
	s_and_saveexec_b64 vcc, s[4:5]
	s_cbranch_execz .LBB0_637
	v_readlane_b32 s26, v255, 5
	s_waitcnt lgkmcnt(0)
	v_add_f32_e32 v20, v18, v19
	v_lshlrev_b64 v[18:19], 6, v[222:223]
	v_readlane_b32 s27, v255, 6
	s_lshl_b32 s46, s43, 2
	s_nop 0
	v_lshl_add_u64 v[18:19], s[26:27], 0, v[18:19]
	v_lshl_add_u64 v[18:19], s[82:83], 2, v[18:19]
	v_lshl_add_u64 v[18:19], v[18:19], 0, s[46:47]
	global_store_dword v[18:19], v20, off

;     DI void operator()(const f32x4 (&acc)[2][2][4][2], const Unit& u, int wr, int wc, int fr, int fq) const {
;     ...
;                     ss += (x0[0] * x0[0] + x0[1] * x0[1]) + (x0[2] * x0[2] + x0[3] * x0[3]) + (x1[0] * x1[0] + x1[1] * x1[1]) + (x1[2] * x1[2] + x1[3] * x1[3]);
;                 }
;                 if (rss) { ss += __shfl_xor(ss, 16); ss += __shfl_xor(ss, 32); if (fq == 0) rss[(size_t)row * 16 + u.pn * 4 + wc] = ss; }
.LBB0_646:
	s_and_b64 vcc, exec, s[12:13]
	s_cbranch_vccnz .LBB0_650
	v_mul_f32_e32 v15, v15, v15
	v_mul_f32_e32 v5, v5, v5
	v_mul_f32_e32 v3, v3, v3
	v_fmac_f32_e32 v15, v14, v14
	v_mul_f32_e32 v14, v17, v17
	v_fmac_f32_e32 v5, v4, v4
	v_fmac_f32_e32 v3, v2, v2
	v_mul_f32_e32 v2, v7, v7
	v_mul_f32_e32 v4, v9, v9
	v_fmac_f32_e32 v14, v16, v16
	v_mul_f32_e32 v11, v11, v11
	v_fmac_f32_e32 v2, v6, v6
	v_fmac_f32_e32 v4, v8, v8
	v_add_f32_e32 v14, v15, v14
	v_fmac_f32_e32 v11, v10, v10
	v_add_f32_e32 v2, v2, v4
	v_and_b32_e32 v4, 64, v245
	v_add_f32_e32 v10, v11, v14
	v_mul_f32_e32 v11, v13, v13
	v_add_f32_e32 v2, v3, v2
	v_add_u32_e32 v4, 64, v4
	v_fmac_f32_e32 v11, v12, v12
	v_add_f32_e32 v10, v11, v10
	v_add_f32_e32 v2, v5, v2
	v_add_f32_e32 v2, v10, v2
	v_mov_b32_e32 v3, v2
	s_nop 1
	v_permlane16_swap_b32_e32 v3, v2
	s_waitcnt lgkmcnt(0)
	v_add_f32_e32 v2, v2, v3
	s_nop 1
	v_mov_b32_e32 v3, v2
	s_nop 1
	v_permlane32_swap_b32_e32 v3, v2
	s_and_saveexec_b64 s[8:9], s[4:5]
	s_cbranch_execz .LBB0_649
	v_readlane_b32 s10, v255, 5
	s_waitcnt lgkmcnt(0)
	v_add_f32_e32 v4, v2, v3
	v_lshlrev_b64 v[2:3], 6, v[218:219]
	v_readlane_b32 s11, v255, 6
	s_lshl_b32 s46, s43, 2
	s_nop 0
	v_lshl_add_u64 v[2:3], s[10:11], 0, v[2:3]
	v_lshl_add_u64 v[2:3], s[82:83], 2, v[2:3]
	v_lshl_add_u64 v[2:3], v[2:3], 0, s[46:47]
	global_store_dword v[2:3], v4, off
